# ssm scan step: negate/swap folded into v_pk_mul modifiers (2 fewer VALU ops per step, bit-identical)
# baseline (speedup 1.0000x reference)
; #define MFMA16(a, b, c) __builtin_amdgcn_mfma_f32_16x16x32_bf16((a), (b), (c), 0, 0, 0)
; DI unsigned pk2(float a, float b) { f2_t v = {a, b}; bf2_t r = __builtin_convertvector(v, bf2_t); return __builtin_bit_cast(unsigned, r); }
; DI void ssm_out_item(const CP& p, int l, int item, char* smem) {
;     ...
;       for (int s2 = 0; s2 < 32; ++s2) {
;         const fl2 bu = {__uint_as_float((unsigned)sX[s2 * 136 + lane] << 16), __uint_as_float((unsigned)sX[s2 * 136 + 64 + lane] << 16)};
;         const fl2 xs = {-x.y, x.x};
;         x = x * a_r + xs * a_i + bu;
;         const unsigned pkx = pk2(x.x, x.y);
;         sX[s2 * 136 + lane] = (u16)(pkx & 0xffffu);
;         sX[s2 * 136 + 64 + lane] = (u16)(pkx >> 16);
;       }
;       __syncthreads();
;       f32x4v ya[2];
; #pragma unroll
;       for (int nb = 0; nb < 2; ++nb) {
;         ya[nb] = (f32x4v){0.f, 0.f, 0.f, 0.f};
; #pragma unroll
;         for (int ks = 0; ks < 4; ++ks) {
;           bf16x8 xb = *(const bf16x8*)(sX + (nb * 16 + l16) * 136 + ks * 32 + q4 * 8);
;           ya[nb] = MFMA16(cf[ks], xb, ya[nb]);
;         }
;       }
; #pragma unroll
;       for (int nb = 0; nb < 2; ++nb) {
;         const int s = sub * 32 + nb * 16 + l16;
;         const u32x2 uu = *(const u32x2*)(p.R + (tok0 + s) * TMW + 1408 + g * 16 + q4 * 4);
.LBB0_334:
	v_add_u32_e32 v6, s39, v32
	ds_read_u16 v100, v6
	ds_read_u16 v101, v6 offset:128
	ds_read_u16 v102, v6 offset:272
	ds_read_u16 v103, v6 offset:400
	ds_read_u16 v104, v6 offset:544
	ds_read_u16 v105, v6 offset:672
	ds_read_u16 v106, v6 offset:816
	ds_read_u16 v107, v6 offset:944
	s_addk_i32 s39, 0x880
	v_pk_mul_f32 v[2:3], v[74:75], v[82:83] op_sel:[0,1] op_sel_hi:[1,0] neg_lo:[0,1]
	s_waitcnt lgkmcnt(6)
	v_lshlrev_b32_e32 v100, 16, v100
	v_lshlrev_b32_e32 v101, 16, v101
	v_pk_fma_f32 v[2:3], v[80:81], v[82:83], v[2:3]
	s_nop 0
	v_pk_add_f32 v[0:1], v[2:3], v[100:101]
	s_nop 0
	v_cvt_pk_bf16_f32 v2, v0, v1
	ds_write_b16 v6, v2
	ds_write_b16_d16_hi v6, v2 offset:128
	v_pk_mul_f32 v[4:5], v[74:75], v[0:1] op_sel:[0,1] op_sel_hi:[1,0] neg_lo:[0,1]
	s_waitcnt lgkmcnt(6)
	v_lshlrev_b32_e32 v102, 16, v102
	v_lshlrev_b32_e32 v103, 16, v103
	v_pk_fma_f32 v[0:1], v[80:81], v[0:1], v[4:5]
	s_nop 0
	v_pk_add_f32 v[0:1], v[0:1], v[102:103]
	s_nop 0
	v_cvt_pk_bf16_f32 v2, v0, v1
	ds_write_b16 v6, v2 offset:272
	ds_write_b16_d16_hi v6, v2 offset:400
	v_pk_mul_f32 v[4:5], v[74:75], v[0:1] op_sel:[0,1] op_sel_hi:[1,0] neg_lo:[0,1]
	s_waitcnt lgkmcnt(6)
	v_lshlrev_b32_e32 v104, 16, v104
	v_lshlrev_b32_e32 v105, 16, v105
	v_pk_fma_f32 v[0:1], v[80:81], v[0:1], v[4:5]
	s_nop 0
	v_pk_add_f32 v[0:1], v[0:1], v[104:105]
	s_nop 0
	v_cvt_pk_bf16_f32 v2, v0, v1
	ds_write_b16 v6, v2 offset:544
	ds_write_b16_d16_hi v6, v2 offset:672
	v_pk_mul_f32 v[4:5], v[74:75], v[0:1] op_sel:[0,1] op_sel_hi:[1,0] neg_lo:[0,1]
	s_waitcnt lgkmcnt(6)
	v_lshlrev_b32_e32 v106, 16, v106
	v_lshlrev_b32_e32 v107, 16, v107
	v_pk_fma_f32 v[0:1], v[80:81], v[0:1], v[4:5]
	s_nop 0
	v_pk_add_f32 v[0:1], v[0:1], v[106:107]
	s_nop 0
	v_cvt_pk_bf16_f32 v2, v0, v1
	ds_write_b16 v6, v2 offset:816
	ds_write_b16_d16_hi v6, v2 offset:944
	ds_read_u16 v108, v6 offset:1088
	ds_read_u16 v109, v6 offset:1216
	ds_read_u16 v110, v6 offset:1360
	ds_read_u16 v111, v6 offset:1488
	ds_read_u16 v112, v6 offset:1632
	ds_read_u16 v113, v6 offset:1760
	ds_read_u16 v114, v6 offset:1904
	ds_read_u16 v115, v6 offset:2032
	v_pk_mul_f32 v[4:5], v[74:75], v[0:1] op_sel:[0,1] op_sel_hi:[1,0] neg_lo:[0,1]
	s_waitcnt lgkmcnt(6)
	v_lshlrev_b32_e32 v108, 16, v108
	v_lshlrev_b32_e32 v109, 16, v109
	v_pk_fma_f32 v[0:1], v[80:81], v[0:1], v[4:5]
	s_nop 0
	v_pk_add_f32 v[0:1], v[0:1], v[108:109]
	s_nop 0
	v_cvt_pk_bf16_f32 v2, v0, v1
	ds_write_b16 v6, v2 offset:1088
	ds_write_b16_d16_hi v6, v2 offset:1216
	v_pk_mul_f32 v[4:5], v[74:75], v[0:1] op_sel:[0,1] op_sel_hi:[1,0] neg_lo:[0,1]
	s_waitcnt lgkmcnt(6)
	v_lshlrev_b32_e32 v110, 16, v110
	v_lshlrev_b32_e32 v111, 16, v111
	v_pk_fma_f32 v[0:1], v[80:81], v[0:1], v[4:5]
	s_nop 0
	v_pk_add_f32 v[0:1], v[0:1], v[110:111]
	s_nop 0
	v_cvt_pk_bf16_f32 v2, v0, v1
	ds_write_b16 v6, v2 offset:1360
	ds_write_b16_d16_hi v6, v2 offset:1488
	v_pk_mul_f32 v[4:5], v[74:75], v[0:1] op_sel:[0,1] op_sel_hi:[1,0] neg_lo:[0,1]
	s_waitcnt lgkmcnt(6)
	v_lshlrev_b32_e32 v112, 16, v112
	v_lshlrev_b32_e32 v113, 16, v113
	v_pk_fma_f32 v[0:1], v[80:81], v[0:1], v[4:5]
	s_nop 0
	v_pk_add_f32 v[0:1], v[0:1], v[112:113]
	s_nop 0
	v_cvt_pk_bf16_f32 v2, v0, v1
	ds_write_b16 v6, v2 offset:1632
	ds_write_b16_d16_hi v6, v2 offset:1760
	v_pk_mul_f32 v[4:5], v[74:75], v[0:1] op_sel:[0,1] op_sel_hi:[1,0] neg_lo:[0,1]
	s_waitcnt lgkmcnt(6)
	v_lshlrev_b32_e32 v114, 16, v114
	v_lshlrev_b32_e32 v115, 16, v115
	v_pk_fma_f32 v[0:1], v[80:81], v[0:1], v[4:5]
	s_nop 0
	v_pk_add_f32 v[82:83], v[0:1], v[114:115]
	s_nop 0
	v_cvt_pk_bf16_f32 v0, v82, v83
	ds_write_b16 v6, v0 offset:1904
	ds_write_b16_d16_hi v6, v0 offset:2032
	s_cmpk_eq_i32 s39, 0x2200
	s_cbranch_scc0 .LBB0_334
	s_waitcnt lgkmcnt(0)
	s_barrier
	ds_read_b128 v[0:3], v88
	ds_read_b128 v[4:7], v88 offset:64
	s_waitcnt lgkmcnt(1)
	v_mfma_f32_16x16x32_bf16 v[0:3], v[34:37], v[0:3], 0
	ds_read_b128 v[10:13], v88 offset:4416
	s_mov_b64 s[72:73], 0
	s_waitcnt lgkmcnt(1)
	v_mfma_f32_16x16x32_bf16 v[0:3], v[38:41], v[4:7], v[0:3]
	ds_read_b128 v[4:7], v88 offset:128
	s_waitcnt lgkmcnt(0)
	v_mfma_f32_16x16x32_bf16 v[0:3], v[42:45], v[4:7], v[0:3]
	ds_read_b128 v[4:7], v88 offset:192
	s_waitcnt lgkmcnt(0)
	v_mfma_f32_16x16x32_bf16 v[6:9], v[46:49], v[4:7], v[0:3]
	v_or_b32_e32 v5, s38, v84
	s_nop 3
	ds_read_b128 v[0:3], v88 offset:4352
	v_or_b32_e32 v4, s6, v5
	s_waitcnt lgkmcnt(0)
	v_mfma_f32_16x16x32_bf16 v[0:3], v[34:37], v[0:3], 0
	v_mfma_f32_16x16x32_bf16 v[0:3], v[38:41], v[10:13], v[0:3]
	ds_read_b128 v[10:13], v88 offset:4480
	s_waitcnt lgkmcnt(0)
	v_mfma_f32_16x16x32_bf16 v[0:3], v[42:45], v[10:13], v[0:3]
	ds_read_b128 v[10:13], v88 offset:4544
	s_waitcnt lgkmcnt(0)
	v_mfma_f32_16x16x32_bf16 v[0:3], v[46:49], v[10:13], v[0:3]
	v_mad_u64_u32 v[10:11], s[38:39], v4, s45, v[78:79]
	v_mad_u32_u24 v11, s7, v212, v11
	global_load_dwordx2 v[10:11], v[10:11], off offset:2816
	v_or_b32_e32 v4, 16, v4
	s_waitcnt vmcnt(0)
; DI unsigned pk2(float a, float b) { f2_t v = {a, b}; bf2_t r = __builtin_convertvector(v, bf2_t); return __builtin_bit_cast(unsigned, r); }
; DI float bflo(unsigned u) { return __uint_as_float(u << 16); }
; DI float bfhi(unsigned u) { return __uint_as_float(u & 0xffff0000u); }
; DI float gelu_tanh(float x) {
;   const float u = 0.7978845608028654f * (x + 0.044715f * x * x * x);
;   const float e = __expf(2.f * u);
;   const float th = 1.f - 2.f / (e + 1.f);
;   return 0.5f * x * (1.f + th);
; }
; DI void ssm_out_item(const CP& p, int l, int item, char* smem) {
;     ...
; #pragma unroll
;       for (int nb = 0; nb < 2; ++nb) {
;         const int s = sub * 32 + nb * 16 + l16;
;         const u32x2 uu = *(const u32x2*)(p.R + (tok0 + s) * TMW + 1408 + g * 16 + q4 * 4);
;         const float y0 = gelu_tanh(ya[nb][0] + dsk.x * bflo(uu.x));
;         const float y1 = gelu_tanh(ya[nb][1] + dsk.y * bfhi(uu.x));
;         const float y2 = gelu_tanh(ya[nb][2] + dsk.z * bflo(uu.y));
;         const float y3 = gelu_tanh(ya[nb][3] + dsk.w * bfhi(uu.y));
;         u32x2 v;
;         v.x = pk2(y0, y1); v.y = pk2(y2, y3);
;         *(u32x2*)(sY + s * 264 + g * 16 + q4 * 4) = v;
;       }
;       __syncthreads();
	v_lshlrev_b32_e32 v12, 16, v10
	v_and_b32_e32 v13, 0xffff0000, v10
	v_pk_fma_f32 v[6:7], v[50:51], v[12:13], v[6:7]
	s_nop 0
	v_mul_f32_e32 v10, 0x3d372713, v6
	v_mul_f32_e32 v10, v6, v10
	v_fma_f32 v10, v6, v10, v6
	v_mul_f32_e32 v10, 0x3f4c422a, v10
	v_add_f32_e32 v10, v10, v10
	v_mul_f32_e32 v10, 0x3fb8aa3b, v10
	v_exp_f32_e32 v12, v10
	v_mul_f32_e32 v10, 0x3d372713, v7
	v_mul_f32_e32 v10, v7, v10
	v_fma_f32 v10, v7, v10, v7
	v_mul_f32_e32 v10, 0x3f4c422a, v10
	v_add_f32_e32 v10, v10, v10
	v_mul_f32_e32 v10, 0x3fb8aa3b, v10
	v_exp_f32_e32 v13, v10
	v_pk_mul_f32 v[6:7], v[6:7], 0.5 op_sel_hi:[1,0]
	v_pk_add_f32 v[12:13], v[12:13], 1.0 op_sel_hi:[1,0]
	s_nop 0
	v_div_scale_f32 v10, s[38:39], v13, v13, 2.0
	v_rcp_f32_e32 v14, v10
	s_nop 0
	v_fma_f32 v15, -v10, v14, 1.0
	v_fmac_f32_e32 v14, v15, v14
	v_div_scale_f32 v15, vcc, 2.0, v13, 2.0
	v_mul_f32_e32 v90, v15, v14
	v_fma_f32 v91, -v10, v90, v15
	v_fmac_f32_e32 v90, v91, v14
	v_fma_f32 v10, -v10, v90, v15
	v_div_fmas_f32 v10, v10, v14, v90
	v_div_fixup_f32 v13, v10, v13, 2.0
	v_div_scale_f32 v10, s[38:39], v12, v12, 2.0
	v_rcp_f32_e32 v14, v10
	s_nop 0
	v_fma_f32 v15, -v10, v14, 1.0
	v_fmac_f32_e32 v14, v15, v14
	v_div_scale_f32 v15, vcc, 2.0, v12, 2.0
	v_mul_f32_e32 v90, v15, v14
	v_fma_f32 v91, -v10, v90, v15
	v_fmac_f32_e32 v90, v91, v14
	v_fma_f32 v10, -v10, v90, v15
	v_div_fmas_f32 v10, v10, v14, v90
	v_div_fixup_f32 v12, v10, v12, 2.0
	v_lshlrev_b32_e32 v10, 16, v11
	v_and_b32_e32 v11, 0xffff0000, v11
	v_pk_fma_f32 v[8:9], v[52:53], v[10:11], v[8:9]
	v_pk_add_f32 v[12:13], v[12:13], 1.0 op_sel_hi:[1,0] neg_lo:[1,0] neg_hi:[1,0]
	v_mul_f32_e32 v10, 0x3d372713, v8
	v_mul_f32_e32 v11, 0x3d372713, v9
	v_mul_f32_e32 v10, v8, v10
	v_mul_f32_e32 v11, v9, v11
	v_fma_f32 v10, v8, v10, v8
	v_fma_f32 v11, v9, v11, v9
	v_mul_f32_e32 v10, 0x3f4c422a, v10
	v_mul_f32_e32 v11, 0x3f4c422a, v11
	v_add_f32_e32 v10, v10, v10
	v_add_f32_e32 v11, v11, v11
	v_mul_f32_e32 v10, 0x3fb8aa3b, v10
	v_mul_f32_e32 v11, 0x3fb8aa3b, v11
	v_exp_f32_e32 v10, v10
	v_exp_f32_e32 v11, v11
	v_pk_add_f32 v[12:13], v[12:13], 1.0 op_sel_hi:[1,0]
	v_pk_mul_f32 v[8:9], v[8:9], 0.5 op_sel_hi:[1,0]
	v_pk_mul_f32 v[6:7], v[6:7], v[12:13]
	v_pk_add_f32 v[10:11], v[10:11], 1.0 op_sel_hi:[1,0]
	s_nop 0
	v_div_scale_f32 v12, s[38:39], v11, v11, 2.0
	v_rcp_f32_e32 v13, v12
	s_nop 0
	v_fma_f32 v14, -v12, v13, 1.0
	v_fmac_f32_e32 v13, v14, v13
	v_div_scale_f32 v14, vcc, 2.0, v11, 2.0
	v_mul_f32_e32 v15, v14, v13
	v_fma_f32 v90, -v12, v15, v14
	v_fmac_f32_e32 v15, v90, v13
	v_fma_f32 v12, -v12, v15, v14
	v_div_fmas_f32 v12, v12, v13, v15
	v_div_fixup_f32 v11, v12, v11, 2.0
	v_div_scale_f32 v12, s[38:39], v10, v10, 2.0
	v_rcp_f32_e32 v13, v12
	s_nop 0
	v_fma_f32 v14, -v12, v13, 1.0
	v_fmac_f32_e32 v13, v14, v13
	v_div_scale_f32 v14, vcc, 2.0, v10, 2.0
	v_mul_f32_e32 v15, v14, v13
	v_fma_f32 v90, -v12, v15, v14
	v_fmac_f32_e32 v15, v90, v13
	v_fma_f32 v12, -v12, v15, v14
	v_div_fmas_f32 v12, v12, v13, v15
	v_div_fixup_f32 v10, v12, v10, 2.0
	v_pk_add_f32 v[10:11], v[10:11], 1.0 op_sel_hi:[1,0] neg_lo:[1,0] neg_hi:[1,0]
	s_nop 0
	v_pk_add_f32 v[10:11], v[10:11], 1.0 op_sel_hi:[1,0]
	s_nop 0
	v_pk_mul_f32 v[8:9], v[8:9], v[10:11]
	v_cvt_pk_bf16_f32 v10, v6, v7
	v_mad_u32_u24 v6, v5, s88, v89
	v_mad_u64_u32 v[4:5], s[38:39], v4, s45, v[78:79]
	v_mad_u32_u24 v5, s7, v212, v5
	global_load_dwordx2 v[4:5], v[4:5], off offset:2816
	v_cvt_pk_bf16_f32 v11, v8, v9
	ds_write_b64 v6, v[10:11]
	s_waitcnt vmcnt(0)
	v_lshlrev_b32_e32 v8, 16, v4
	v_and_b32_e32 v9, 0xffff0000, v4
	v_pk_fma_f32 v[0:1], v[50:51], v[8:9], v[0:1]
	s_nop 0
	v_mul_f32_e32 v4, 0x3d372713, v0
	v_mul_f32_e32 v4, v0, v4
	v_fma_f32 v4, v0, v4, v0
	v_mul_f32_e32 v4, 0x3f4c422a, v4
	v_add_f32_e32 v4, v4, v4
	v_mul_f32_e32 v4, 0x3fb8aa3b, v4
	v_exp_f32_e32 v8, v4
	v_mul_f32_e32 v4, 0x3d372713, v1
	v_mul_f32_e32 v4, v1, v4
	v_fma_f32 v4, v1, v4, v1
	v_mul_f32_e32 v4, 0x3f4c422a, v4
	v_add_f32_e32 v4, v4, v4
	v_mul_f32_e32 v4, 0x3fb8aa3b, v4
	v_exp_f32_e32 v9, v4
	v_pk_mul_f32 v[0:1], v[0:1], 0.5 op_sel_hi:[1,0]
	v_pk_add_f32 v[8:9], v[8:9], 1.0 op_sel_hi:[1,0]
	s_nop 0
	v_div_scale_f32 v4, s[38:39], v9, v9, 2.0
	v_rcp_f32_e32 v7, v4
	s_nop 0
	v_fma_f32 v10, -v4, v7, 1.0
	v_fmac_f32_e32 v7, v10, v7
	v_div_scale_f32 v10, vcc, 2.0, v9, 2.0
	v_mul_f32_e32 v11, v10, v7
	v_fma_f32 v12, -v4, v11, v10
	v_fmac_f32_e32 v11, v12, v7
	v_fma_f32 v4, -v4, v11, v10
	v_div_fmas_f32 v4, v4, v7, v11
	v_div_fixup_f32 v9, v4, v9, 2.0
	v_div_scale_f32 v4, s[38:39], v8, v8, 2.0
	v_rcp_f32_e32 v7, v4
	s_nop 0
	v_fma_f32 v10, -v4, v7, 1.0
	v_fmac_f32_e32 v7, v10, v7
	v_div_scale_f32 v10, vcc, 2.0, v8, 2.0
	v_mul_f32_e32 v11, v10, v7
	v_fma_f32 v12, -v4, v11, v10
	v_fmac_f32_e32 v11, v12, v7
	v_fma_f32 v4, -v4, v11, v10
	v_div_fmas_f32 v4, v4, v7, v11
	v_div_fixup_f32 v8, v4, v8, 2.0
	v_lshlrev_b32_e32 v4, 16, v5
	v_and_b32_e32 v5, 0xffff0000, v5
	v_pk_fma_f32 v[2:3], v[52:53], v[4:5], v[2:3]
	v_pk_add_f32 v[8:9], v[8:9], 1.0 op_sel_hi:[1,0] neg_lo:[1,0] neg_hi:[1,0]
	v_mul_f32_e32 v4, 0x3d372713, v2
	v_mul_f32_e32 v5, 0x3d372713, v3
	v_mul_f32_e32 v4, v2, v4
	v_mul_f32_e32 v5, v3, v5
	v_fma_f32 v4, v2, v4, v2
	v_fma_f32 v5, v3, v5, v3
	v_mul_f32_e32 v4, 0x3f4c422a, v4
	v_mul_f32_e32 v5, 0x3f4c422a, v5
	v_add_f32_e32 v4, v4, v4
	v_add_f32_e32 v5, v5, v5
	v_mul_f32_e32 v4, 0x3fb8aa3b, v4
	v_mul_f32_e32 v5, 0x3fb8aa3b, v5
	v_exp_f32_e32 v4, v4
	v_exp_f32_e32 v5, v5
	v_pk_add_f32 v[8:9], v[8:9], 1.0 op_sel_hi:[1,0]
	v_pk_mul_f32 v[2:3], v[2:3], 0.5 op_sel_hi:[1,0]
	v_pk_mul_f32 v[0:1], v[0:1], v[8:9]
	v_pk_add_f32 v[4:5], v[4:5], 1.0 op_sel_hi:[1,0]
	v_cvt_pk_bf16_f32 v0, v0, v1
	v_div_scale_f32 v7, s[38:39], v5, v5, 2.0
	v_rcp_f32_e32 v8, v7
	s_nop 0
	v_fma_f32 v9, -v7, v8, 1.0
	v_fmac_f32_e32 v8, v9, v8
	v_div_scale_f32 v9, vcc, 2.0, v5, 2.0
	v_mul_f32_e32 v10, v9, v8
	v_fma_f32 v11, -v7, v10, v9
	v_fmac_f32_e32 v10, v11, v8
	v_fma_f32 v7, -v7, v10, v9
	v_div_fmas_f32 v7, v7, v8, v10
	v_div_fixup_f32 v5, v7, v5, 2.0
	v_div_scale_f32 v7, s[38:39], v4, v4, 2.0
	v_rcp_f32_e32 v8, v7
	s_mov_b32 s38, 32
	v_fma_f32 v9, -v7, v8, 1.0
	v_fmac_f32_e32 v8, v9, v8
	v_div_scale_f32 v9, vcc, 2.0, v4, 2.0
	v_mul_f32_e32 v10, v9, v8
	v_fma_f32 v11, -v7, v10, v9
	v_fmac_f32_e32 v10, v11, v8
	v_fma_f32 v7, -v7, v10, v9
	v_div_fmas_f32 v7, v7, v8, v10
	v_div_fixup_f32 v4, v7, v4, 2.0
	v_pk_add_f32 v[4:5], v[4:5], 1.0 op_sel_hi:[1,0] neg_lo:[1,0] neg_hi:[1,0]
	s_and_b64 vcc, exec, s[70:71]
	v_pk_add_f32 v[4:5], v[4:5], 1.0 op_sel_hi:[1,0]
	s_nop 0
	v_pk_mul_f32 v[2:3], v[2:3], v[4:5]
	s_nop 0
	v_cvt_pk_bf16_f32 v1, v2, v3
	ds_write_b64 v6, v[0:1] offset:8448
	s_waitcnt lgkmcnt(0)
	s_barrier
; DI void ssm_out_item(const CP& p, int l, int item, char* smem) {
;     ...
;       __builtin_amdgcn_wave_barrier();
; #pragma unroll 8
;       for (int s2 = 0; s2 < 32; ++s2) {
;         const fl2 bu = {__uint_as_float((unsigned)sX[s2 * 136 + lane] << 16), __uint_as_float((unsigned)sX[s2 * 136 + 64 + lane] << 16)};
;         const fl2 xs = {-x.y, x.x};
;         x = x * a_r + xs * a_i + bu;
;         const unsigned pkx = pk2(x.x, x.y);
;         sX[s2 * 136 + lane] = (u16)(pkx & 0xffffu);
;         sX[s2 * 136 + 64 + lane] = (u16)(pkx >> 16);
;       }
;       __syncthreads();
;       f32x4v ya[2];
; #pragma unroll
;       for (int nb = 0; nb < 2; ++nb) {
;         ya[nb] = (f32x4v){0.f, 0.f, 0.f, 0.f};
; #pragma unroll
;         for (int ks = 0; ks < 4; ++ks) {
;           bf16x8 xb = *(const bf16x8*)(sX + (nb * 16 + l16) * 136 + ks * 32 + q4 * 8);
;           ya[nb] = MFMA16(cf[ks], xb, ya[nb]);
;         }
;       }
; #pragma unroll
;       for (int nb = 0; nb < 2; ++nb) {
;         const int s = sub * 32 + nb * 16 + l16;
;         const u32x2 uu = *(const u32x2*)(p.R + (tok0 + s) * TMW + 1408 + g * 16 + q4 * 4);
;         const float y0 = gelu_tanh(ya[nb][0] + dsk.x * bflo(uu.x));
;         const float y1 = gelu_tanh(ya[nb][1] + dsk.y * bfhi(uu.x));
;         const float y2 = gelu_tanh(ya[nb][2] + dsk.z * bflo(uu.y));
;         const float y3 = gelu_tanh(ya[nb][3] + dsk.w * bfhi(uu.y));
;         u32x2 v;
;         v.x = pk2(y0, y1); v.y = pk2(y2, y3);
;         *(u32x2*)(sY + s * 264 + g * 16 + q4 * 4) = v;
;       }
;       __syncthreads();
;     }
;   }
;   __syncthreads();
;   f32x16 acc[2];
; #pragma unroll
;   for (int j = 0; j < 2; ++j)
; #pragma unroll
;     for (int r = 0; r < 16; ++r) acc[j][r] = 0.f;
;   const u16* wg = p.wt_glu + (size_t)l * 65536;
; #pragma unroll
;   for (int ks = 0; ks < 16; ++ks) {
;     bf16x8 fa, fb[2];
;     fa = *(const bf16x8*)(wg + (size_t)(w * 32 + l32) * 256 + ks * 16 + hh * 8);
; #pragma unroll
;     for (int i = 0; i < 2; ++i) fb[i] = *(const bf16x8*)(sY + (i * 32 + l32) * 264 + ks * 16 + hh * 8);
; #pragma unroll
;     for (int j = 0; j < 2; ++j) acc[j] = MFMA32(fa, fb[j], acc[j]);
;   }
;   const float* bg = p.b_glu + (size_t)l * 256;
; #pragma unroll
;   for (int j = 0; j < 2; ++j) {
;     const int token = j * 32 + l32;
;     float sq = 0.f;
; #pragma unroll
;     for (int blk = 0; blk < 4; ++blk) {
	s_cbranch_vccz .LBB0_333
	s_mov_b32 s38, 1
	s_mov_b64 s[70:71], 0
	s_and_b64 vcc, exec, s[10:11]
	s_cbranch_vccz .LBB0_332
	v_lshlrev_b32_e32 v37, 5, v59
	v_or_b32_e32 v0, v37, v56
	v_ashrrev_i32_e32 v1, 31, v0
	v_lshlrev_b64 v[0:1], 9, v[0:1]
	v_lshl_add_u64 v[0:1], s[30:31], 0, v[0:1]
	v_lshlrev_b32_e32 v32, 1, v58
	v_lshl_add_u64 v[34:35], v[0:1], 0, v[32:33]
	s_barrier
	global_load_dwordx4 v[100:103], v[34:35], off
	global_load_dwordx4 v[104:107], v[34:35], off offset:32
	global_load_dwordx4 v[108:111], v[34:35], off offset:64
	global_load_dwordx4 v[112:115], v[34:35], off offset:96
	global_load_dwordx4 v[116:119], v[34:35], off offset:128
	global_load_dwordx4 v[120:123], v[34:35], off offset:160
	global_load_dwordx4 v[124:127], v[34:35], off offset:192
	global_load_dwordx4 v[128:131], v[34:35], off offset:224
	global_load_dwordx4 v[132:135], v[34:35], off offset:256
	global_load_dwordx4 v[136:139], v[34:35], off offset:288
	global_load_dwordx4 v[140:143], v[34:35], off offset:320
	global_load_dwordx4 v[144:147], v[34:35], off offset:352
	global_load_dwordx4 v[148:151], v[34:35], off offset:384
	global_load_dwordx4 v[168:171], v[34:35], off offset:416
	global_load_dwordx4 v[172:175], v[34:35], off offset:448
	global_load_dwordx4 v[176:179], v[34:35], off offset:480
	v_add_u32_e32 v4, s44, v32
	v_mad_u32_u24 v50, v56, s88, v4
	v_mad_u32_u24 v32, v56, s88, v213
	v_add_u32_e32 v51, v4, v32
	v_mul_u32_u24_e32 v36, 0x210, v56
	v_cmp_gt_u32_e64 s[4:5], 32, v55
	ds_read_b128 v[180:183], v50
	ds_read_b128 v[184:187], v51
	ds_read_b128 v[188:191], v50 offset:32
	ds_read_b128 v[192:195], v51 offset:32
	s_waitcnt vmcnt(15) lgkmcnt(2)
	v_mfma_f32_32x32x16_bf16 v[16:31], v[100:103], v[180:183], 0
	v_mfma_f32_32x32x16_bf16 v[0:15], v[100:103], v[184:187], 0
	ds_read_b128 v[180:183], v50 offset:64
	ds_read_b128 v[184:187], v51 offset:64
	s_waitcnt vmcnt(14) lgkmcnt(2)
	v_mfma_f32_32x32x16_bf16 v[16:31], v[104:107], v[188:191], v[16:31]
	v_mfma_f32_32x32x16_bf16 v[0:15], v[104:107], v[192:195], v[0:15]
	ds_read_b128 v[188:191], v50 offset:96
	ds_read_b128 v[192:195], v51 offset:96
	s_waitcnt vmcnt(13) lgkmcnt(2)
	v_mfma_f32_32x32x16_bf16 v[16:31], v[108:111], v[180:183], v[16:31]
	v_mfma_f32_32x32x16_bf16 v[0:15], v[108:111], v[184:187], v[0:15]
	ds_read_b128 v[180:183], v50 offset:128
	ds_read_b128 v[184:187], v51 offset:128
	s_waitcnt vmcnt(12) lgkmcnt(2)
	v_mfma_f32_32x32x16_bf16 v[16:31], v[112:115], v[188:191], v[16:31]
	v_mfma_f32_32x32x16_bf16 v[0:15], v[112:115], v[192:195], v[0:15]
	ds_read_b128 v[188:191], v50 offset:160
	ds_read_b128 v[192:195], v51 offset:160
	s_waitcnt vmcnt(11) lgkmcnt(2)
	v_mfma_f32_32x32x16_bf16 v[16:31], v[116:119], v[180:183], v[16:31]
	v_mfma_f32_32x32x16_bf16 v[0:15], v[116:119], v[184:187], v[0:15]
	ds_read_b128 v[180:183], v50 offset:192
	ds_read_b128 v[184:187], v51 offset:192
	s_waitcnt vmcnt(10) lgkmcnt(2)
	v_mfma_f32_32x32x16_bf16 v[16:31], v[120:123], v[188:191], v[16:31]
	v_mfma_f32_32x32x16_bf16 v[0:15], v[120:123], v[192:195], v[0:15]
	ds_read_b128 v[188:191], v50 offset:224
	ds_read_b128 v[192:195], v51 offset:224
	s_waitcnt vmcnt(9) lgkmcnt(2)
	v_mfma_f32_32x32x16_bf16 v[16:31], v[124:127], v[180:183], v[16:31]
	v_mfma_f32_32x32x16_bf16 v[0:15], v[124:127], v[184:187], v[0:15]
	ds_read_b128 v[180:183], v50 offset:256
	ds_read_b128 v[184:187], v51 offset:256
	s_waitcnt vmcnt(8) lgkmcnt(2)
	v_mfma_f32_32x32x16_bf16 v[16:31], v[128:131], v[188:191], v[16:31]
	v_mfma_f32_32x32x16_bf16 v[0:15], v[128:131], v[192:195], v[0:15]
	ds_read_b128 v[188:191], v50 offset:288
	ds_read_b128 v[192:195], v51 offset:288
	s_waitcnt vmcnt(7) lgkmcnt(2)
	v_mfma_f32_32x32x16_bf16 v[16:31], v[132:135], v[180:183], v[16:31]
	v_mfma_f32_32x32x16_bf16 v[0:15], v[132:135], v[184:187], v[0:15]
	ds_read_b128 v[180:183], v50 offset:320
	ds_read_b128 v[184:187], v51 offset:320
	s_waitcnt vmcnt(6) lgkmcnt(2)
	v_mfma_f32_32x32x16_bf16 v[16:31], v[136:139], v[188:191], v[16:31]
	v_mfma_f32_32x32x16_bf16 v[0:15], v[136:139], v[192:195], v[0:15]
	ds_read_b128 v[188:191], v50 offset:352
	ds_read_b128 v[192:195], v51 offset:352
	s_waitcnt vmcnt(5) lgkmcnt(2)
	v_mfma_f32_32x32x16_bf16 v[16:31], v[140:143], v[180:183], v[16:31]
	v_mfma_f32_32x32x16_bf16 v[0:15], v[140:143], v[184:187], v[0:15]
	ds_read_b128 v[180:183], v50 offset:384
	ds_read_b128 v[184:187], v51 offset:384
	s_waitcnt vmcnt(4) lgkmcnt(2)
	v_mfma_f32_32x32x16_bf16 v[16:31], v[144:147], v[188:191], v[16:31]
	v_mfma_f32_32x32x16_bf16 v[0:15], v[144:147], v[192:195], v[0:15]
	ds_read_b128 v[188:191], v50 offset:416
	ds_read_b128 v[192:195], v51 offset:416
	s_waitcnt vmcnt(3) lgkmcnt(2)
	v_mfma_f32_32x32x16_bf16 v[16:31], v[148:151], v[180:183], v[16:31]
	v_mfma_f32_32x32x16_bf16 v[0:15], v[148:151], v[184:187], v[0:15]
	ds_read_b128 v[180:183], v50 offset:448
	ds_read_b128 v[184:187], v51 offset:448
	s_waitcnt vmcnt(2) lgkmcnt(2)
	v_mfma_f32_32x32x16_bf16 v[16:31], v[168:171], v[188:191], v[16:31]
	v_mfma_f32_32x32x16_bf16 v[0:15], v[168:171], v[192:195], v[0:15]
	ds_read_b128 v[188:191], v50 offset:480
	ds_read_b128 v[192:195], v51 offset:480
	s_waitcnt vmcnt(1) lgkmcnt(2)
	v_mfma_f32_32x32x16_bf16 v[16:31], v[172:175], v[180:183], v[16:31]
	v_mfma_f32_32x32x16_bf16 v[0:15], v[172:175], v[184:187], v[0:15]
	s_waitcnt vmcnt(0) lgkmcnt(0)
	v_mfma_f32_32x32x16_bf16 v[16:31], v[176:179], v[188:191], v[16:31]
	v_mfma_f32_32x32x16_bf16 v[0:15], v[176:179], v[192:195], v[0:15]
	v_and_b32_e32 v34, 0x3fffffc0, v54
	v_mov_b32_e32 v35, s7
	v_lshl_or_b32 v40, v57, 2, v37
	v_ashrrev_i32_e32 v41, 31, v40
	v_lshl_add_u64 v[38:39], v[40:41], 2, s[68:69]
	global_load_dwordx4 v[50:53], v[38:39], off
	v_lshl_add_u32 v48, v34, 2, s36
	v_or_b32_e32 v34, s6, v56
	v_lshlrev_b64 v[34:35], 11, v[34:35]
	v_lshl_add_u64 v[44:45], s[66:67], 0, v[34:35]
	v_lshlrev_b32_e32 v34, 1, v40
	v_add3_u32 v46, s44, v36, v34
	ds_read2_b64 v[34:37], v46 offset1:2
	v_lshl_add_u64 v[44:45], v[40:41], 1, v[44:45]
	s_waitcnt vmcnt(0)
; DI unsigned pk2(float a, float b) { f2_t v = {a, b}; bf2_t r = __builtin_convertvector(v, bf2_t); return __builtin_bit_cast(unsigned, r); }
; DI float bflo(unsigned u) { return __uint_as_float(u << 16); }
; DI float bfhi(unsigned u) { return __uint_as_float(u & 0xffff0000u); }
; DI void ssm_out_item(const CP& p, int l, int item, char* smem) {
;     ...
; #pragma unroll
;     for (int blk = 0; blk < 4; ++blk) {
;       const int ch = w * 32 + 8 * blk + 4 * hh;
;       const fl4 bv = *(const fl4*)(bg + ch);
;       const u32x2 yy = *(const u32x2*)(sY + token * 264 + ch);
;       const float g0 = 1.f / (1.f + __expf(-(acc[j][4 * blk] + bv.x)));
;       const float g1 = 1.f / (1.f + __expf(-(acc[j][4 * blk + 1] + bv.y)));
;       const float g2 = 1.f / (1.f + __expf(-(acc[j][4 * blk + 2] + bv.z)));
;       const float g3 = 1.f / (1.f + __expf(-(acc[j][4 * blk + 3] + bv.w)));
;       const float o0 = bflo(yy.x) * g0, o1 = bfhi(yy.x) * g1, o2 = bflo(yy.y) * g2, o3 = bfhi(yy.y) * g3;
;       sq += o0 * o0 + o1 * o1 + o2 * o2 + o3 * o3;
;       u32x2 v;
;       v.x = pk2(o0, o1); v.y = pk2(o2, o3);
;       *(u32x2*)(p.mixed + (tok0 + token) * 1024 + 768 + ch) = v;
;     }
	v_add_f32_e32 v16, v16, v50
	v_add_f32_e32 v17, v17, v51
	v_mul_f32_e32 v16, 0xbfb8aa3b, v16
	v_mul_f32_e32 v17, 0xbfb8aa3b, v17
	v_exp_f32_e32 v16, v16
	v_exp_f32_e32 v17, v17
	v_add_f32_e32 v18, v18, v52
	v_add_f32_e32 v19, v19, v53
	v_mul_f32_e32 v18, 0xbfb8aa3b, v18
	v_pk_add_f32 v[16:17], v[16:17], 1.0 op_sel_hi:[1,0]
	v_mul_f32_e32 v19, 0xbfb8aa3b, v19
	v_div_scale_f32 v42, s[10:11], v17, v17, 1.0
	v_rcp_f32_e32 v43, v42
	v_exp_f32_e32 v18, v18
	v_exp_f32_e32 v19, v19
	v_fma_f32 v47, -v42, v43, 1.0
	v_fmac_f32_e32 v43, v47, v43
	v_div_scale_f32 v47, vcc, 1.0, v17, 1.0
	v_mul_f32_e32 v49, v47, v43
	v_fma_f32 v50, -v42, v49, v47
	v_fmac_f32_e32 v49, v50, v43
	v_fma_f32 v42, -v42, v49, v47
	v_div_fmas_f32 v42, v42, v43, v49
	v_div_fixup_f32 v17, v42, v17, 1.0
	v_div_scale_f32 v42, s[10:11], v16, v16, 1.0
	v_rcp_f32_e32 v43, v42
	v_pk_add_f32 v[18:19], v[18:19], 1.0 op_sel_hi:[1,0]
	v_fma_f32 v47, -v42, v43, 1.0
	v_fmac_f32_e32 v43, v47, v43
	v_div_scale_f32 v47, vcc, 1.0, v16, 1.0
	v_mul_f32_e32 v49, v47, v43
	v_fma_f32 v50, -v42, v49, v47
	v_fmac_f32_e32 v49, v50, v43
	v_fma_f32 v42, -v42, v49, v47
	v_div_fmas_f32 v42, v42, v43, v49
	v_div_fixup_f32 v16, v42, v16, 1.0
	s_waitcnt lgkmcnt(0)
	v_lshlrev_b32_e32 v42, 16, v34
	v_and_b32_e32 v43, 0xffff0000, v34
	v_div_scale_f32 v34, s[10:11], v19, v19, 1.0
	v_pk_mul_f32 v[16:17], v[16:17], v[42:43]
	v_rcp_f32_e32 v42, v34
	s_nop 0
	v_fma_f32 v43, -v34, v42, 1.0
	v_fmac_f32_e32 v42, v43, v42
	v_div_scale_f32 v43, vcc, 1.0, v19, 1.0
	v_mul_f32_e32 v47, v43, v42
	v_fma_f32 v49, -v34, v47, v43
	v_fmac_f32_e32 v47, v49, v42
	v_fma_f32 v34, -v34, v47, v43
	v_div_fmas_f32 v34, v34, v42, v47
	v_div_fixup_f32 v19, v34, v19, 1.0
	v_div_scale_f32 v34, s[10:11], v18, v18, 1.0
	v_rcp_f32_e32 v42, v34
	s_nop 0
	v_fma_f32 v43, -v34, v42, 1.0
	v_fmac_f32_e32 v42, v43, v42
	v_div_scale_f32 v43, vcc, 1.0, v18, 1.0
	v_mul_f32_e32 v47, v43, v42
	v_fma_f32 v49, -v34, v47, v43
	v_fmac_f32_e32 v47, v49, v42
	v_fma_f32 v34, -v34, v47, v43
	v_div_fmas_f32 v34, v34, v42, v47
	v_div_fixup_f32 v18, v34, v18, 1.0
	v_lshlrev_b32_e32 v34, 16, v35
	v_and_b32_e32 v35, 0xffff0000, v35
	v_pk_mul_f32 v[18:19], v[18:19], v[34:35]
	v_pk_mul_f32 v[42:43], v[16:17], v[16:17]
	v_cvt_pk_bf16_f32 v16, v16, v17
	v_cvt_pk_bf16_f32 v17, v18, v19
	global_store_dwordx2 v[44:45], v[16:17], off offset:1536
	v_pk_mul_f32 v[34:35], v[18:19], v[18:19]
	global_load_dwordx4 v[16:19], v[38:39], off offset:32
	s_waitcnt vmcnt(0)
	v_add_f32_e32 v16, v20, v16
	v_add_f32_e32 v17, v21, v17
	v_mul_f32_e32 v16, 0xbfb8aa3b, v16
	v_mul_f32_e32 v17, 0xbfb8aa3b, v17
	v_exp_f32_e32 v16, v16
	v_exp_f32_e32 v17, v17
	v_add_f32_e32 v18, v22, v18
	v_mul_f32_e32 v18, 0xbfb8aa3b, v18
	v_exp_f32_e32 v20, v18
	v_add_f32_e32 v18, v23, v19
	v_mul_f32_e32 v18, 0xbfb8aa3b, v18
	v_pk_add_f32 v[16:17], v[16:17], 1.0 op_sel_hi:[1,0]
	v_exp_f32_e32 v21, v18
	v_div_scale_f32 v18, s[10:11], v17, v17, 1.0
	v_rcp_f32_e32 v19, v18
	v_pk_add_f32 v[20:21], v[20:21], 1.0 op_sel_hi:[1,0]
	v_fma_f32 v22, -v18, v19, 1.0
	v_fmac_f32_e32 v19, v22, v19
	v_div_scale_f32 v22, vcc, 1.0, v17, 1.0
	v_mul_f32_e32 v23, v22, v19
	v_fma_f32 v47, -v18, v23, v22
	v_fmac_f32_e32 v23, v47, v19
	v_fma_f32 v18, -v18, v23, v22
	v_div_fmas_f32 v18, v18, v19, v23
	v_div_fixup_f32 v23, v18, v17, 1.0
	v_div_scale_f32 v17, s[10:11], v16, v16, 1.0
	v_rcp_f32_e32 v18, v17
	s_nop 0
	v_fma_f32 v19, -v17, v18, 1.0
	v_fmac_f32_e32 v18, v19, v18
	v_div_scale_f32 v19, vcc, 1.0, v16, 1.0
	v_mul_f32_e32 v22, v19, v18
	v_fma_f32 v47, -v17, v22, v19
	v_fmac_f32_e32 v22, v47, v18
	v_fma_f32 v17, -v17, v22, v19
	v_div_fmas_f32 v17, v17, v18, v22
	v_div_fixup_f32 v22, v17, v16, 1.0
	ds_read2_b64 v[16:19], v46 offset0:4 offset1:6
	v_lshlrev_b32_e32 v46, 16, v36
	v_and_b32_e32 v47, 0xffff0000, v36
	v_pk_mul_f32 v[46:47], v[22:23], v[46:47]
	v_div_scale_f32 v22, s[10:11], v21, v21, 1.0
	v_rcp_f32_e32 v23, v22
	s_nop 0
	v_fma_f32 v36, -v22, v23, 1.0
	v_fmac_f32_e32 v23, v36, v23
	v_div_scale_f32 v36, vcc, 1.0, v21, 1.0
	v_mul_f32_e32 v49, v36, v23
	v_fma_f32 v50, -v22, v49, v36
	v_fmac_f32_e32 v49, v50, v23
	v_fma_f32 v22, -v22, v49, v36
	v_div_fmas_f32 v22, v22, v23, v49
	v_div_fixup_f32 v21, v22, v21, 1.0
	v_div_scale_f32 v22, s[10:11], v20, v20, 1.0
	v_rcp_f32_e32 v23, v22
	s_nop 0
	v_fma_f32 v36, -v22, v23, 1.0
	v_fmac_f32_e32 v23, v36, v23
	v_div_scale_f32 v36, vcc, 1.0, v20, 1.0
	v_mul_f32_e32 v49, v36, v23
	v_fma_f32 v50, -v22, v49, v36
	v_fmac_f32_e32 v49, v50, v23
	v_fma_f32 v22, -v22, v49, v36
	v_div_fmas_f32 v22, v22, v23, v49
	v_div_fixup_f32 v20, v22, v20, 1.0
	v_lshlrev_b32_e32 v22, 16, v37
	v_and_b32_e32 v23, 0xffff0000, v37
	v_pk_mul_f32 v[36:37], v[20:21], v[22:23]
	v_pk_mul_f32 v[22:23], v[46:47], v[46:47]
	v_cvt_pk_bf16_f32 v46, v46, v47
	v_cvt_pk_bf16_f32 v47, v36, v37
	global_store_dwordx2 v[44:45], v[46:47], off offset:1552
	global_load_dwordx4 v[50:53], v[38:39], off offset:64
	v_pk_mul_f32 v[20:21], v[36:37], v[36:37]
	v_add_f32_e32 v22, v22, v23
	v_add_f32_e32 v20, v20, v22
	v_add_f32_e32 v20, v21, v20
	s_waitcnt vmcnt(0)
; DI unsigned pk2(float a, float b) { f2_t v = {a, b}; bf2_t r = __builtin_convertvector(v, bf2_t); return __builtin_bit_cast(unsigned, r); }
; DI float bflo(unsigned u) { return __uint_as_float(u << 16); }
; DI float bfhi(unsigned u) { return __uint_as_float(u & 0xffff0000u); }
; DI float shx32(float v) { return shx(v, get_tid() & 63, 32); }
; DI void ssm_out_item(const CP& p, int l, int item, char* smem) {
;     ...
; #pragma unroll
;     for (int blk = 0; blk < 4; ++blk) {
;       const int ch = w * 32 + 8 * blk + 4 * hh;
;       const fl4 bv = *(const fl4*)(bg + ch);
;       const u32x2 yy = *(const u32x2*)(sY + token * 264 + ch);
;       const float g0 = 1.f / (1.f + __expf(-(acc[j][4 * blk] + bv.x)));
;       const float g1 = 1.f / (1.f + __expf(-(acc[j][4 * blk + 1] + bv.y)));
;       const float g2 = 1.f / (1.f + __expf(-(acc[j][4 * blk + 2] + bv.z)));
;       const float g3 = 1.f / (1.f + __expf(-(acc[j][4 * blk + 3] + bv.w)));
;       const float o0 = bflo(yy.x) * g0, o1 = bfhi(yy.x) * g1, o2 = bflo(yy.y) * g2, o3 = bfhi(yy.y) * g3;
;       sq += o0 * o0 + o1 * o1 + o2 * o2 + o3 * o3;
;       u32x2 v;
;       v.x = pk2(o0, o1); v.y = pk2(o2, o3);
;       *(u32x2*)(p.mixed + (tok0 + token) * 1024 + 768 + ch) = v;
;     }
;     sq += shx32(sq);
;     if (hh == 0) sSS[w * 64 + token] = sq;
	v_add_f32_e32 v24, v24, v50
	v_add_f32_e32 v25, v25, v51
	v_mul_f32_e32 v24, 0xbfb8aa3b, v24
	v_mul_f32_e32 v25, 0xbfb8aa3b, v25
	v_exp_f32_e32 v24, v24
	v_exp_f32_e32 v25, v25
	v_add_f32_e32 v26, v26, v52
	v_add_f32_e32 v27, v27, v53
	v_mul_f32_e32 v26, 0xbfb8aa3b, v26
	v_pk_add_f32 v[24:25], v[24:25], 1.0 op_sel_hi:[1,0]
	v_mul_f32_e32 v27, 0xbfb8aa3b, v27
	v_div_scale_f32 v36, s[10:11], v25, v25, 1.0
	v_rcp_f32_e32 v37, v36
	v_exp_f32_e32 v26, v26
	v_exp_f32_e32 v27, v27
	v_fma_f32 v46, -v36, v37, 1.0
	v_fmac_f32_e32 v37, v46, v37
	v_div_scale_f32 v46, vcc, 1.0, v25, 1.0
	v_mul_f32_e32 v47, v46, v37
	v_fma_f32 v49, -v36, v47, v46
	v_fmac_f32_e32 v47, v49, v37
	v_fma_f32 v36, -v36, v47, v46
	v_div_fmas_f32 v36, v36, v37, v47
	v_div_fixup_f32 v25, v36, v25, 1.0
	v_div_scale_f32 v36, s[10:11], v24, v24, 1.0
	v_rcp_f32_e32 v37, v36
	v_pk_add_f32 v[26:27], v[26:27], 1.0 op_sel_hi:[1,0]
	v_fma_f32 v46, -v36, v37, 1.0
	v_fmac_f32_e32 v37, v46, v37
	v_div_scale_f32 v46, vcc, 1.0, v24, 1.0
	v_mul_f32_e32 v47, v46, v37
	v_fma_f32 v49, -v36, v47, v46
	v_fmac_f32_e32 v47, v49, v37
	v_fma_f32 v36, -v36, v47, v46
	v_div_fmas_f32 v36, v36, v37, v47
	v_div_fixup_f32 v24, v36, v24, 1.0
	s_waitcnt lgkmcnt(0)
	v_lshlrev_b32_e32 v36, 16, v16
	v_and_b32_e32 v37, 0xffff0000, v16
	v_div_scale_f32 v16, s[10:11], v27, v27, 1.0
	v_pk_mul_f32 v[24:25], v[24:25], v[36:37]
	v_rcp_f32_e32 v36, v16
	s_nop 0
	v_fma_f32 v37, -v16, v36, 1.0
	v_fmac_f32_e32 v36, v37, v36
	v_div_scale_f32 v37, vcc, 1.0, v27, 1.0
	v_mul_f32_e32 v46, v37, v36
	v_fma_f32 v47, -v16, v46, v37
	v_fmac_f32_e32 v46, v47, v36
	v_fma_f32 v16, -v16, v46, v37
	v_div_fmas_f32 v16, v16, v36, v46
	v_div_fixup_f32 v27, v16, v27, 1.0
	v_div_scale_f32 v16, s[10:11], v26, v26, 1.0
	v_rcp_f32_e32 v36, v16
	s_nop 0
	v_fma_f32 v37, -v16, v36, 1.0
	v_fmac_f32_e32 v36, v37, v36
	v_div_scale_f32 v37, vcc, 1.0, v26, 1.0
	v_mul_f32_e32 v46, v37, v36
	v_fma_f32 v47, -v16, v46, v37
	v_fmac_f32_e32 v46, v47, v36
	v_fma_f32 v16, -v16, v46, v37
	v_div_fmas_f32 v16, v16, v36, v46
	v_div_fixup_f32 v26, v16, v26, 1.0
	v_lshlrev_b32_e32 v16, 16, v17
	v_and_b32_e32 v17, 0xffff0000, v17
	v_pk_mul_f32 v[36:37], v[26:27], v[16:17]
	v_pk_mul_f32 v[26:27], v[24:25], v[24:25]
	v_cvt_pk_bf16_f32 v24, v24, v25
	v_cvt_pk_bf16_f32 v25, v36, v37
	global_store_dwordx2 v[44:45], v[24:25], off offset:1568
	global_load_dwordx4 v[50:53], v[38:39], off offset:96
	v_pk_mul_f32 v[16:17], v[36:37], v[36:37]
	v_add_f32_e32 v21, v26, v27
	v_add_f32_e32 v16, v16, v21
	v_add_f32_e32 v16, v17, v16
	v_lshl_add_u32 v26, v56, 2, v48
	s_waitcnt vmcnt(0)
	v_add_f32_e32 v24, v28, v50
	v_add_f32_e32 v25, v29, v51
	v_mul_f32_e32 v24, 0xbfb8aa3b, v24
	v_mul_f32_e32 v25, 0xbfb8aa3b, v25
	v_exp_f32_e32 v24, v24
	v_exp_f32_e32 v25, v25
	v_add_f32_e32 v28, v30, v52
	v_add_f32_e32 v29, v31, v53
	v_mul_f32_e32 v28, 0xbfb8aa3b, v28
	v_pk_add_f32 v[24:25], v[24:25], 1.0 op_sel_hi:[1,0]
	v_mul_f32_e32 v29, 0xbfb8aa3b, v29
	v_div_scale_f32 v30, s[10:11], v25, v25, 1.0
	v_rcp_f32_e32 v31, v30
	v_exp_f32_e32 v28, v28
	v_exp_f32_e32 v29, v29
	v_fma_f32 v36, -v30, v31, 1.0
	v_fmac_f32_e32 v31, v36, v31
	v_div_scale_f32 v36, vcc, 1.0, v25, 1.0
	v_mul_f32_e32 v37, v36, v31
	v_fma_f32 v46, -v30, v37, v36
	v_fmac_f32_e32 v37, v46, v31
	v_fma_f32 v30, -v30, v37, v36
	v_div_fmas_f32 v30, v30, v31, v37
	v_div_fixup_f32 v25, v30, v25, 1.0
	v_div_scale_f32 v30, s[10:11], v24, v24, 1.0
	v_rcp_f32_e32 v31, v30
	v_pk_add_f32 v[28:29], v[28:29], 1.0 op_sel_hi:[1,0]
	v_fma_f32 v36, -v30, v31, 1.0
	v_fmac_f32_e32 v31, v36, v31
	v_div_scale_f32 v36, vcc, 1.0, v24, 1.0
	v_mul_f32_e32 v37, v36, v31
	v_fma_f32 v46, -v30, v37, v36
	v_fmac_f32_e32 v37, v46, v31
	v_fma_f32 v30, -v30, v37, v36
	v_div_fmas_f32 v30, v30, v31, v37
	v_div_fixup_f32 v24, v30, v24, 1.0
	v_lshlrev_b32_e32 v30, 16, v18
	v_and_b32_e32 v31, 0xffff0000, v18
	v_div_scale_f32 v18, s[10:11], v29, v29, 1.0
	v_pk_mul_f32 v[24:25], v[24:25], v[30:31]
	v_rcp_f32_e32 v30, v18
	s_nop 0
	v_fma_f32 v31, -v18, v30, 1.0
	v_fmac_f32_e32 v30, v31, v30
	v_div_scale_f32 v31, vcc, 1.0, v29, 1.0
	v_mul_f32_e32 v36, v31, v30
	v_fma_f32 v37, -v18, v36, v31
	v_fmac_f32_e32 v36, v37, v30
	v_fma_f32 v18, -v18, v36, v31
	v_div_fmas_f32 v18, v18, v30, v36
	v_div_fixup_f32 v29, v18, v29, 1.0
	v_div_scale_f32 v18, s[10:11], v28, v28, 1.0
	v_rcp_f32_e32 v30, v18
	s_nop 0
	v_fma_f32 v31, -v18, v30, 1.0
	v_fmac_f32_e32 v30, v31, v30
	v_div_scale_f32 v31, vcc, 1.0, v28, 1.0
	v_mul_f32_e32 v36, v31, v30
	v_fma_f32 v37, -v18, v36, v31
	v_fmac_f32_e32 v36, v37, v30
	v_fma_f32 v18, -v18, v36, v31
	v_div_fmas_f32 v18, v18, v30, v36
	v_div_fixup_f32 v28, v18, v28, 1.0
	v_lshlrev_b32_e32 v18, 16, v19
	v_and_b32_e32 v19, 0xffff0000, v19
	v_add_f32_e32 v36, v42, v43
	v_pk_mul_f32 v[18:19], v[28:29], v[18:19]
	v_pk_mul_f32 v[28:29], v[24:25], v[24:25]
	v_add_f32_e32 v34, v34, v36
	v_pk_mul_f32 v[30:31], v[18:19], v[18:19]
	v_add_f32_e32 v34, v35, v34
	v_add_f32_e32 v17, v28, v29
	v_add_f32_e32 v20, v34, v20
	v_add_f32_e32 v17, v30, v17
	v_add_f32_e32 v16, v20, v16
	v_add_f32_e32 v17, v31, v17
	v_add_f32_e32 v16, v16, v17
	v_cvt_pk_bf16_f32 v20, v24, v25
	v_cvt_pk_bf16_f32 v21, v18, v19
	v_mov_b32_e32 v17, v202
	global_store_dwordx2 v[44:45], v[20:21], off offset:1584
	s_nop 0
	v_lshlrev_b32_e32 v17, 2, v17
	v_bitop3_b32 v17, v17, s84, v211 bitop3:0x6c
	ds_bpermute_b32 v17, v17, v16
	s_and_saveexec_b64 s[10:11], s[4:5]
	s_cbranch_execz .LBB0_339
	s_waitcnt lgkmcnt(0)
	v_add_f32_e32 v16, v16, v17
	ds_write_b32 v26, v16
